# P8 SwiGLU epilogue: row-norm partial loads software-pipelined one tile ahead, quarter sums gathered by bpermute, eight rows computed stage-wise with no waits
# speedup vs baseline: 1.0188x; 1.0099x over previous
.LBB0_541:
	s_mov_b64 s[16:17], 0x80
	s_and_b32 s9, s0, 3
	s_add_i32 m0, s48, 0x18000
	v_lshl_add_u64 v[6:7], v[6:7], 0, s[16:17]
	s_lshl_b32 s24, s7, 13
	s_lshl_b32 s25, s9, 12
	s_waitcnt vmcnt(2)
	s_barrier
	global_load_lds_dwordx4 v[6:7], off
	v_lshl_add_u64 v[4:5], v[4:5], 0, s[16:17]
	s_add_i32 m0, s48, 0x1a000
	s_add_i32 s53, s48, 0x8000
	s_add_i32 s54, s48, 0xa000
	global_load_lds_dwordx4 v[4:5], off
	v_lshl_add_u64 v[0:1], v[0:1], 0, s[16:17]
	s_mov_b32 m0, s53
	s_add_u32 s18, s12, 0x40080
	global_load_lds_dwordx4 v[0:1], off
	v_lshl_add_u64 v[0:1], v[2:3], 0, s[16:17]
	s_mov_b32 m0, s54
	s_addc_u32 s19, s13, 0
	global_load_lds_dwordx4 v[0:1], off
	s_add_i32 m0, s48, 0x1c000
	v_lshl_add_u64 v[0:1], s[18:19], 0, v[132:133]
	global_load_lds_dwordx4 v[0:1], off
	v_lshl_add_u64 v[0:1], s[18:19], 0, v[128:129]
	s_add_i32 m0, s48, 0x1e000
	s_cmpk_lt_u32 s1, 0x100
	global_load_lds_dwordx4 v[0:1], off
	v_bfe_u32 v1, v10, 4, 2
	v_and_b32_e32 v0, 15, v10
	v_lshlrev_b32_e32 v2, 4, v1
	v_lshl_or_b32 v146, s7, 6, v0
	v_lshl_or_b32 v0, v0, 6, v2
	v_lshlrev_b32_e32 v2, 2, v10
	v_and_b32_e32 v2, 32, v2
	v_bitop3_b32 v3, v0, s24, v2 bitop3:0xde
	v_bitop3_b32 v147, v0, s25, v2 bitop3:0xde
	v_lshlrev_b32_e32 v0, 2, v1
	v_lshl_or_b32 v148, s9, 4, v0
	v_lshlrev_b32_e32 v0, 14, v13
	v_and_b32_e32 v0, 0xffff8000, v0
	v_lshl_add_u32 v0, v12, 11, v0
	v_and_b32_e32 v1, 1, v13
	v_lshl_or_b32 v0, v1, 6, v0
	v_lshl_add_u32 v136, v14, 1, v0
	v_lshlrev_b32_e32 v0, 14, v8
	v_and_b32_e32 v0, 0xffff8000, v0
	s_waitcnt vmcnt(6)
	v_lshl_add_u32 v0, v9, 11, v0
	v_and_b32_e32 v1, 1, v8
	s_cselect_b64 s[18:19], -1, 0
	v_lshl_or_b32 v0, v1, 6, v0
	s_add_i32 s56, 0, 0x10000
	s_add_i32 s57, 0, 0x14000
	s_sext_i32_i16 s0, s6
	s_ashr_i32 s55, s33, 31
	v_mov_b32_e32 v137, v133
	v_lshl_add_u32 v138, v11, 1, v0
	v_mov_b32_e32 v139, v133
	v_add_u32_e32 v149, s56, v147
	v_add_u32_e32 v150, s57, v147
	v_add_u32_e32 v151, 0, v3
	v_mov_b32_e32 v152, 0x358637bd
	s_mov_b32 s58, 0x800000
	s_movk_i32 s59, 0x1600
	s_mov_b64 s[42:43], s[12:13]
	s_mov_b64 s[36:37], s[10:11]
	s_barrier
	v_lshl_add_u32 v144, s8, 8, v146
	v_bfe_u32 v145, v254, 4, 2
	v_lshlrev_b32_e32 v144, 6, v144
	v_lshl_add_u32 v144, v145, 4, v144
	v_add_u32_e32 v145, 0x2000, v144
	global_load_dwordx4 v[226:229], v144, s[40:41]
	global_load_dwordx4 v[230:233], v144, s[40:41] offset:1024
	global_load_dwordx4 v[234:237], v144, s[40:41] offset:2048
	global_load_dwordx4 v[238:241], v144, s[40:41] offset:3072
	global_load_dwordx4 v[242:245], v145, s[40:41]
	global_load_dwordx4 v[246:249], v145, s[40:41] offset:1024
	global_load_dwordx4 v[250:253], v145, s[40:41] offset:2048
	global_load_dwordx4 v[140:143], v145, s[40:41] offset:3072
	s_branch .LBB0_544

.LBB0_544:
	s_add_i32 s52, s52, 1
	s_mul_i32 s1, s52, s55
	s_mul_hi_u32 s6, s52, s33
	s_add_i32 s6, s6, s1
	s_mul_i32 s1, s52, s33
	s_add_u32 s44, s1, s2
	s_addc_u32 s45, s6, s3
	s_cmpk_lt_i32 s44, 0xb00
	s_cselect_b64 s[6:7], -1, 0
	s_cbranch_scc0 .LBB0_546
	s_ashr_i32 s1, s44, 31
	s_lshr_b32 s1, s1, 29
	s_add_i32 s1, s44, s1
	s_ashr_i32 s9, s1, 3
	s_and_b32 s1, s1, -8
	s_sub_i32 s1, s44, s1
	s_cmp_lt_i32 s1, 0
	s_cselect_b32 s24, s47, 0x160
	s_mul_i32 s1, s1, s24
	s_add_i32 s1, s1, s9
	s_mul_hi_i32 s9, s1, 0x2e8ba2e9
	s_lshr_b32 s24, s9, 31
	s_ashr_i32 s9, s9, 5
	s_add_i32 s9, s9, s24
	s_lshl_b32 s25, s9, 3
	s_sub_i32 s24, 0x80, s25
	s_min_i32 s26, s24, 8
	s_abs_i32 s24, s26
	v_cvt_f32_u32_e32 v0, s24
	s_sub_i32 s28, 0, s24
	s_mulk_i32 s9, 0xb0
	s_sub_i32 s1, s1, s9
	v_rcp_iflag_f32_e32 v0, v0
	s_abs_i32 s9, s1
	s_xor_b32 s27, s1, s26
	s_ashr_i32 s27, s27, 31
	v_mul_f32_e32 v0, 0x4f7ffffe, v0
	v_cvt_u32_f32_e32 v0, v0
	s_nop 0
	v_readfirstlane_b32 s29, v0
	s_mul_i32 s28, s28, s29
	s_mul_hi_u32 s28, s29, s28
	s_add_i32 s29, s29, s28
	s_mul_hi_u32 s28, s9, s29
	s_mul_i32 s29, s28, s24
	s_sub_i32 s9, s9, s29
	s_add_i32 s36, s28, 1
	s_sub_i32 s29, s9, s24
	s_cmp_ge_u32 s9, s24
	s_cselect_b32 s28, s36, s28
	s_cselect_b32 s9, s29, s9
	s_add_i32 s29, s28, 1
	s_cmp_ge_u32 s9, s24
	s_cselect_b32 s9, s29, s28
	s_xor_b32 s9, s9, s27
	s_sub_i32 s24, s9, s27
	s_mul_i32 s9, s24, s26
	s_sub_i32 s1, s1, s9
	s_add_i32 s28, s25, s1
	s_ashr_i32 s29, s28, 31
	s_lshl_b64 s[26:27], s[28:29], 19
	s_add_u32 s36, s38, s26
	s_addc_u32 s37, s39, s27
	s_ashr_i32 s25, s24, 31
	s_lshl_b64 s[26:27], s[24:25], 19
	s_add_u32 s42, s22, s26
	s_addc_u32 s43, s23, s27

.LBB0_550:
	v_add_f32_e32 v166, v226, v227
	v_add_f32_e32 v167, v230, v231
	v_add_f32_e32 v168, v234, v235
	v_add_f32_e32 v169, v238, v239
	v_add_f32_e32 v170, v242, v243
	v_add_f32_e32 v171, v246, v247
	v_add_f32_e32 v172, v250, v251
	v_add_f32_e32 v173, v140, v141
	v_add_f32_e32 v214, v228, v229
	v_add_f32_e32 v215, v232, v233
	v_add_f32_e32 v216, v236, v237
	v_add_f32_e32 v217, v240, v241
	v_add_f32_e32 v218, v244, v245
	v_add_f32_e32 v219, v248, v249
	v_add_f32_e32 v220, v252, v253
	v_add_f32_e32 v221, v142, v143
	v_and_b32_e32 v162, 15, v254
	v_lshlrev_b32_e32 v162, 2, v162
	v_add_u32_e32 v163, 64, v162
	v_add_u32_e32 v164, 128, v162
	v_add_u32_e32 v165, 192, v162
	v_add_f32_e32 v166, v166, v214
	v_add_f32_e32 v167, v167, v215
	v_add_f32_e32 v168, v168, v216
	v_add_f32_e32 v169, v169, v217
	v_add_f32_e32 v170, v170, v218
	v_add_f32_e32 v171, v171, v219
	v_add_f32_e32 v172, v172, v220
	v_add_f32_e32 v173, v173, v221
	ds_bpermute_b32 v174, v162, v166
	ds_bpermute_b32 v175, v163, v166
	ds_bpermute_b32 v176, v164, v166
	ds_bpermute_b32 v177, v165, v166
	ds_bpermute_b32 v178, v162, v167
	ds_bpermute_b32 v179, v163, v167
	ds_bpermute_b32 v180, v164, v167
	ds_bpermute_b32 v181, v165, v167
	ds_bpermute_b32 v182, v162, v168
	ds_bpermute_b32 v183, v163, v168
	ds_bpermute_b32 v184, v164, v168
	ds_bpermute_b32 v185, v165, v168
	ds_bpermute_b32 v186, v162, v169
	ds_bpermute_b32 v187, v163, v169
	ds_bpermute_b32 v188, v164, v169
	ds_bpermute_b32 v189, v165, v169
	ds_bpermute_b32 v190, v162, v170
	ds_bpermute_b32 v191, v163, v170
	ds_bpermute_b32 v192, v164, v170
	ds_bpermute_b32 v193, v165, v170
	ds_bpermute_b32 v194, v162, v171
	ds_bpermute_b32 v195, v163, v171
	ds_bpermute_b32 v196, v164, v171
	ds_bpermute_b32 v197, v165, v171
	ds_bpermute_b32 v198, v162, v172
	ds_bpermute_b32 v199, v163, v172
	ds_bpermute_b32 v200, v164, v172
	ds_bpermute_b32 v201, v165, v172
	ds_bpermute_b32 v202, v162, v173
	ds_bpermute_b32 v203, v163, v173
	ds_bpermute_b32 v204, v164, v173
	ds_bpermute_b32 v205, v165, v173
	s_cmp_lg_u64 s[6:7], 0
	s_cbranch_scc0 .Lp8_nonext
	v_lshl_add_u32 v144, s28, 8, v146
	v_bfe_u32 v145, v254, 4, 2
	v_lshlrev_b32_e32 v144, 6, v144
	v_lshl_add_u32 v144, v145, 4, v144
	v_add_u32_e32 v145, 0x2000, v144
	global_load_dwordx4 v[226:229], v144, s[40:41]
	global_load_dwordx4 v[230:233], v144, s[40:41] offset:1024
	global_load_dwordx4 v[234:237], v144, s[40:41] offset:2048
	global_load_dwordx4 v[238:241], v144, s[40:41] offset:3072
	global_load_dwordx4 v[242:245], v145, s[40:41]
	global_load_dwordx4 v[246:249], v145, s[40:41] offset:1024
	global_load_dwordx4 v[250:253], v145, s[40:41] offset:2048
	global_load_dwordx4 v[140:143], v145, s[40:41] offset:3072
.Lp8_nonext:
	v_lshl_add_u32 v214, s8, 8, v146
	v_lshl_or_b32 v215, s0, 7, v148
	v_mul_u32_u24_e32 v154, 0x1600, v214
	v_lshl_add_u32 v154, v215, 1, v154
	v_add_u32_e32 v155, 0x16000, v154
	v_add_u32_e32 v156, 0x2c000, v154
	v_add_u32_e32 v157, 0x42000, v154
	v_add_u32_e32 v158, 0xb0000, v154
	v_add_u32_e32 v159, 0xc6000, v154
	v_add_u32_e32 v160, 0xdc000, v154
	v_add_u32_e32 v161, 0xf2000, v154
	s_waitcnt lgkmcnt(0)
	v_add_f32_e32 v174, v174, v175
	v_add_f32_e32 v178, v178, v179
	v_add_f32_e32 v182, v182, v183
	v_add_f32_e32 v186, v186, v187
	v_add_f32_e32 v190, v190, v191
	v_add_f32_e32 v194, v194, v195
	v_add_f32_e32 v198, v198, v199
	v_add_f32_e32 v202, v202, v203
	v_add_f32_e32 v174, v174, v176
	v_add_f32_e32 v178, v178, v180
	v_add_f32_e32 v182, v182, v184
	v_add_f32_e32 v186, v186, v188
	v_add_f32_e32 v190, v190, v192
	v_add_f32_e32 v194, v194, v196
	v_add_f32_e32 v198, v198, v200
	v_add_f32_e32 v202, v202, v204
	v_add_f32_e32 v174, v174, v177
	v_add_f32_e32 v178, v178, v181
	v_add_f32_e32 v182, v182, v185
	v_add_f32_e32 v186, v186, v189
	v_add_f32_e32 v190, v190, v193
	v_add_f32_e32 v194, v194, v197
	v_add_f32_e32 v198, v198, v201
	v_add_f32_e32 v202, v202, v205
	v_fmamk_f32 v174, v174, 0x3a800000, v152
	v_fmamk_f32 v178, v178, 0x3a800000, v152
	v_fmamk_f32 v182, v182, 0x3a800000, v152
	v_fmamk_f32 v186, v186, 0x3a800000, v152
	v_fmamk_f32 v190, v190, 0x3a800000, v152
	v_fmamk_f32 v194, v194, 0x3a800000, v152
	v_fmamk_f32 v198, v198, 0x3a800000, v152
	v_fmamk_f32 v202, v202, 0x3a800000, v152
	v_mul_f32_e32 v175, 0x4b800000, v174
	v_mul_f32_e32 v179, 0x4b800000, v178
	v_mul_f32_e32 v183, 0x4b800000, v182
	v_mul_f32_e32 v187, 0x4b800000, v186
	v_mul_f32_e32 v191, 0x4b800000, v190
	v_mul_f32_e32 v195, 0x4b800000, v194
	v_mul_f32_e32 v199, 0x4b800000, v198
	v_mul_f32_e32 v203, 0x4b800000, v202
	v_cmp_gt_f32_e64 s[74:75], s58, v174
	v_cmp_gt_f32_e64 s[76:77], s58, v178
	v_cmp_gt_f32_e64 s[78:79], s58, v182
	v_cmp_gt_f32_e64 s[80:81], s58, v186
	v_cmp_gt_f32_e64 s[82:83], s58, v190
	v_cmp_gt_f32_e64 s[84:85], s58, v194
	v_cmp_gt_f32_e64 s[86:87], s58, v198
	v_cmp_gt_f32_e64 s[88:89], s58, v202
	v_cndmask_b32_e64 v174, v174, v175, s[74:75]
	v_cndmask_b32_e64 v178, v178, v179, s[76:77]
	v_cndmask_b32_e64 v182, v182, v183, s[78:79]
	v_cndmask_b32_e64 v186, v186, v187, s[80:81]
	v_cndmask_b32_e64 v190, v190, v191, s[82:83]
	v_cndmask_b32_e64 v194, v194, v195, s[84:85]
	v_cndmask_b32_e64 v198, v198, v199, s[86:87]
	v_cndmask_b32_e64 v202, v202, v203, s[88:89]
	v_rsq_f32_e32 v174, v174
	v_rsq_f32_e32 v178, v178
	v_rsq_f32_e32 v182, v182
	v_rsq_f32_e32 v186, v186
	v_rsq_f32_e32 v190, v190
	v_rsq_f32_e32 v194, v194
	v_rsq_f32_e32 v198, v198
	v_rsq_f32_e32 v202, v202
	v_mul_f32_e32 v175, 0x45800000, v174
	v_mul_f32_e32 v179, 0x45800000, v178
	v_mul_f32_e32 v183, 0x45800000, v182
	v_mul_f32_e32 v187, 0x45800000, v186
	v_mul_f32_e32 v191, 0x45800000, v190
	v_mul_f32_e32 v195, 0x45800000, v194
	v_mul_f32_e32 v199, 0x45800000, v198
	v_mul_f32_e32 v203, 0x45800000, v202
	v_cndmask_b32_e64 v206, v174, v175, s[74:75]
	v_cndmask_b32_e64 v207, v178, v179, s[76:77]
	v_cndmask_b32_e64 v208, v182, v183, s[78:79]
	v_cndmask_b32_e64 v209, v186, v187, s[80:81]
	v_cndmask_b32_e64 v210, v190, v191, s[82:83]
	v_cndmask_b32_e64 v211, v194, v195, s[84:85]
	v_cndmask_b32_e64 v212, v198, v199, s[86:87]
	v_cndmask_b32_e64 v213, v202, v203, s[88:89]
	v_mul_f32_e32 v120, v120, v206
	v_mul_f32_e32 v121, v121, v206
	v_mul_f32_e32 v122, v122, v206
	v_mul_f32_e32 v123, v123, v206
	v_mul_f32_e32 v116, v116, v206
	v_mul_f32_e32 v117, v117, v206
	v_mul_f32_e32 v118, v118, v206
	v_mul_f32_e32 v119, v119, v206
	v_mul_f32_e32 v124, v124, v206
	v_mul_f32_e32 v125, v125, v206
	v_mul_f32_e32 v126, v126, v206
	v_mul_f32_e32 v127, v127, v206
	v_mul_f32_e32 v112, v112, v206
	v_mul_f32_e32 v113, v113, v206
	v_mul_f32_e32 v114, v114, v206
	v_mul_f32_e32 v115, v115, v206
	v_mul_f32_e32 v222, 0xbfb8aa3b, v120
	v_mul_f32_e32 v223, 0xbfb8aa3b, v121
	v_mul_f32_e32 v224, 0xbfb8aa3b, v122
	v_mul_f32_e32 v225, 0xbfb8aa3b, v123
	v_mul_f32_e32 v144, 0xbfb8aa3b, v116
	v_mul_f32_e32 v145, 0xbfb8aa3b, v117
	v_mul_f32_e32 v153, 0xbfb8aa3b, v118
	v_mul_f32_e32 v255, 0xbfb8aa3b, v119
	v_exp_f32_e32 v222, v222
	v_exp_f32_e32 v223, v223
	v_exp_f32_e32 v224, v224
	v_exp_f32_e32 v225, v225
	v_exp_f32_e32 v144, v144
	v_exp_f32_e32 v145, v145
	v_exp_f32_e32 v153, v153
	v_exp_f32_e32 v255, v255
	v_add_f32_e32 v222, 1.0, v222
	v_add_f32_e32 v223, 1.0, v223
	v_add_f32_e32 v224, 1.0, v224
	v_add_f32_e32 v225, 1.0, v225
	v_add_f32_e32 v144, 1.0, v144
	v_add_f32_e32 v145, 1.0, v145
	v_add_f32_e32 v153, 1.0, v153
	v_add_f32_e32 v255, 1.0, v255
	v_rcp_f32_e32 v222, v222
	v_rcp_f32_e32 v223, v223
	v_rcp_f32_e32 v224, v224
	v_rcp_f32_e32 v225, v225
	v_rcp_f32_e32 v144, v144
	v_rcp_f32_e32 v145, v145
	v_rcp_f32_e32 v153, v153
	v_rcp_f32_e32 v255, v255
	v_mul_f32_e32 v120, v120, v222
	v_mul_f32_e32 v121, v121, v223
	v_mul_f32_e32 v122, v122, v224
	v_mul_f32_e32 v123, v123, v225
	v_mul_f32_e32 v116, v116, v144
	v_mul_f32_e32 v117, v117, v145
	v_mul_f32_e32 v118, v118, v153
	v_mul_f32_e32 v119, v119, v255
	v_mul_f32_e32 v120, v124, v120
	v_mul_f32_e32 v121, v125, v121
	v_mul_f32_e32 v122, v126, v122
	v_mul_f32_e32 v123, v127, v123
	v_mul_f32_e32 v116, v112, v116
	v_mul_f32_e32 v117, v113, v117
	v_mul_f32_e32 v118, v114, v118
	v_mul_f32_e32 v119, v115, v119
	v_cvt_pk_bf16_f32 v120, v120, v121
	v_cvt_pk_bf16_f32 v121, v122, v123
	v_cvt_pk_bf16_f32 v116, v116, v117
	v_cvt_pk_bf16_f32 v117, v118, v119
	global_store_dwordx2 v154, v[120:121], s[34:35]
	global_store_dwordx2 v154, v[116:117], s[34:35] offset:128
	v_mul_f32_e32 v108, v108, v207
	v_mul_f32_e32 v109, v109, v207
	v_mul_f32_e32 v110, v110, v207
	v_mul_f32_e32 v111, v111, v207
	v_mul_f32_e32 v100, v100, v207
	v_mul_f32_e32 v101, v101, v207
	v_mul_f32_e32 v102, v102, v207
	v_mul_f32_e32 v103, v103, v207
	v_mul_f32_e32 v104, v104, v207
	v_mul_f32_e32 v105, v105, v207
	v_mul_f32_e32 v106, v106, v207
	v_mul_f32_e32 v107, v107, v207
	v_mul_f32_e32 v96, v96, v207
	v_mul_f32_e32 v97, v97, v207
	v_mul_f32_e32 v98, v98, v207
	v_mul_f32_e32 v99, v99, v207
	v_mul_f32_e32 v222, 0xbfb8aa3b, v108
	v_mul_f32_e32 v223, 0xbfb8aa3b, v109
	v_mul_f32_e32 v224, 0xbfb8aa3b, v110
	v_mul_f32_e32 v225, 0xbfb8aa3b, v111
	v_mul_f32_e32 v144, 0xbfb8aa3b, v100
	v_mul_f32_e32 v145, 0xbfb8aa3b, v101
	v_mul_f32_e32 v153, 0xbfb8aa3b, v102
	v_mul_f32_e32 v255, 0xbfb8aa3b, v103
	v_exp_f32_e32 v222, v222
	v_exp_f32_e32 v223, v223
	v_exp_f32_e32 v224, v224
	v_exp_f32_e32 v225, v225
	v_exp_f32_e32 v144, v144
	v_exp_f32_e32 v145, v145
	v_exp_f32_e32 v153, v153
	v_exp_f32_e32 v255, v255
	v_add_f32_e32 v222, 1.0, v222
	v_add_f32_e32 v223, 1.0, v223
	v_add_f32_e32 v224, 1.0, v224
	v_add_f32_e32 v225, 1.0, v225
	v_add_f32_e32 v144, 1.0, v144
	v_add_f32_e32 v145, 1.0, v145
	v_add_f32_e32 v153, 1.0, v153
	v_add_f32_e32 v255, 1.0, v255
	v_rcp_f32_e32 v222, v222
	v_rcp_f32_e32 v223, v223
	v_rcp_f32_e32 v224, v224
	v_rcp_f32_e32 v225, v225
	v_rcp_f32_e32 v144, v144
	v_rcp_f32_e32 v145, v145
	v_rcp_f32_e32 v153, v153
	v_rcp_f32_e32 v255, v255
	v_mul_f32_e32 v108, v108, v222
	v_mul_f32_e32 v109, v109, v223
	v_mul_f32_e32 v110, v110, v224
	v_mul_f32_e32 v111, v111, v225
	v_mul_f32_e32 v100, v100, v144
	v_mul_f32_e32 v101, v101, v145
	v_mul_f32_e32 v102, v102, v153
	v_mul_f32_e32 v103, v103, v255
	v_mul_f32_e32 v108, v104, v108
	v_mul_f32_e32 v109, v105, v109
	v_mul_f32_e32 v110, v106, v110
	v_mul_f32_e32 v111, v107, v111
	v_mul_f32_e32 v100, v96, v100
	v_mul_f32_e32 v101, v97, v101
	v_mul_f32_e32 v102, v98, v102
	v_mul_f32_e32 v103, v99, v103
	v_cvt_pk_bf16_f32 v108, v108, v109
	v_cvt_pk_bf16_f32 v109, v110, v111
	v_cvt_pk_bf16_f32 v100, v100, v101
	v_cvt_pk_bf16_f32 v101, v102, v103
	global_store_dwordx2 v155, v[108:109], s[34:35]
	global_store_dwordx2 v155, v[100:101], s[34:35] offset:128
	v_mul_f32_e32 v92, v92, v208
	v_mul_f32_e32 v93, v93, v208
	v_mul_f32_e32 v94, v94, v208
	v_mul_f32_e32 v95, v95, v208
	v_mul_f32_e32 v84, v84, v208
	v_mul_f32_e32 v85, v85, v208
	v_mul_f32_e32 v86, v86, v208
	v_mul_f32_e32 v87, v87, v208
	v_mul_f32_e32 v88, v88, v208
	v_mul_f32_e32 v89, v89, v208
	v_mul_f32_e32 v90, v90, v208
	v_mul_f32_e32 v91, v91, v208
	v_mul_f32_e32 v80, v80, v208
	v_mul_f32_e32 v81, v81, v208
	v_mul_f32_e32 v82, v82, v208
	v_mul_f32_e32 v83, v83, v208
	v_mul_f32_e32 v222, 0xbfb8aa3b, v92
	v_mul_f32_e32 v223, 0xbfb8aa3b, v93
	v_mul_f32_e32 v224, 0xbfb8aa3b, v94
	v_mul_f32_e32 v225, 0xbfb8aa3b, v95
	v_mul_f32_e32 v144, 0xbfb8aa3b, v84
	v_mul_f32_e32 v145, 0xbfb8aa3b, v85
	v_mul_f32_e32 v153, 0xbfb8aa3b, v86
	v_mul_f32_e32 v255, 0xbfb8aa3b, v87
	v_exp_f32_e32 v222, v222
	v_exp_f32_e32 v223, v223
	v_exp_f32_e32 v224, v224
	v_exp_f32_e32 v225, v225
	v_exp_f32_e32 v144, v144
	v_exp_f32_e32 v145, v145
	v_exp_f32_e32 v153, v153
	v_exp_f32_e32 v255, v255
	v_add_f32_e32 v222, 1.0, v222
	v_add_f32_e32 v223, 1.0, v223
	v_add_f32_e32 v224, 1.0, v224
	v_add_f32_e32 v225, 1.0, v225
	v_add_f32_e32 v144, 1.0, v144
	v_add_f32_e32 v145, 1.0, v145
	v_add_f32_e32 v153, 1.0, v153
	v_add_f32_e32 v255, 1.0, v255
	v_rcp_f32_e32 v222, v222
	v_rcp_f32_e32 v223, v223
	v_rcp_f32_e32 v224, v224
	v_rcp_f32_e32 v225, v225
	v_rcp_f32_e32 v144, v144
	v_rcp_f32_e32 v145, v145
	v_rcp_f32_e32 v153, v153
	v_rcp_f32_e32 v255, v255
	v_mul_f32_e32 v92, v92, v222
	v_mul_f32_e32 v93, v93, v223
	v_mul_f32_e32 v94, v94, v224
	v_mul_f32_e32 v95, v95, v225
	v_mul_f32_e32 v84, v84, v144
	v_mul_f32_e32 v85, v85, v145
	v_mul_f32_e32 v86, v86, v153
	v_mul_f32_e32 v87, v87, v255
	v_mul_f32_e32 v92, v88, v92
	v_mul_f32_e32 v93, v89, v93
	v_mul_f32_e32 v94, v90, v94
	v_mul_f32_e32 v95, v91, v95
	v_mul_f32_e32 v84, v80, v84
	v_mul_f32_e32 v85, v81, v85
	v_mul_f32_e32 v86, v82, v86
	v_mul_f32_e32 v87, v83, v87
	v_cvt_pk_bf16_f32 v92, v92, v93
	v_cvt_pk_bf16_f32 v93, v94, v95
	v_cvt_pk_bf16_f32 v84, v84, v85
	v_cvt_pk_bf16_f32 v85, v86, v87
	global_store_dwordx2 v156, v[92:93], s[34:35]
	global_store_dwordx2 v156, v[84:85], s[34:35] offset:128
	v_mul_f32_e32 v76, v76, v209
	v_mul_f32_e32 v77, v77, v209
	v_mul_f32_e32 v78, v78, v209
	v_mul_f32_e32 v79, v79, v209
	v_mul_f32_e32 v68, v68, v209
	v_mul_f32_e32 v69, v69, v209
	v_mul_f32_e32 v70, v70, v209
	v_mul_f32_e32 v71, v71, v209
	v_mul_f32_e32 v72, v72, v209
	v_mul_f32_e32 v73, v73, v209
	v_mul_f32_e32 v74, v74, v209
	v_mul_f32_e32 v75, v75, v209
	v_mul_f32_e32 v64, v64, v209
	v_mul_f32_e32 v65, v65, v209
	v_mul_f32_e32 v66, v66, v209
	v_mul_f32_e32 v67, v67, v209
	v_mul_f32_e32 v222, 0xbfb8aa3b, v76
	v_mul_f32_e32 v223, 0xbfb8aa3b, v77
	v_mul_f32_e32 v224, 0xbfb8aa3b, v78
	v_mul_f32_e32 v225, 0xbfb8aa3b, v79
	v_mul_f32_e32 v144, 0xbfb8aa3b, v68
	v_mul_f32_e32 v145, 0xbfb8aa3b, v69
	v_mul_f32_e32 v153, 0xbfb8aa3b, v70
	v_mul_f32_e32 v255, 0xbfb8aa3b, v71
	v_exp_f32_e32 v222, v222
	v_exp_f32_e32 v223, v223
	v_exp_f32_e32 v224, v224
	v_exp_f32_e32 v225, v225
	v_exp_f32_e32 v144, v144
	v_exp_f32_e32 v145, v145
	v_exp_f32_e32 v153, v153
	v_exp_f32_e32 v255, v255
	v_add_f32_e32 v222, 1.0, v222
	v_add_f32_e32 v223, 1.0, v223
	v_add_f32_e32 v224, 1.0, v224
	v_add_f32_e32 v225, 1.0, v225
	v_add_f32_e32 v144, 1.0, v144
	v_add_f32_e32 v145, 1.0, v145
	v_add_f32_e32 v153, 1.0, v153
	v_add_f32_e32 v255, 1.0, v255
	v_rcp_f32_e32 v222, v222
	v_rcp_f32_e32 v223, v223
	v_rcp_f32_e32 v224, v224
	v_rcp_f32_e32 v225, v225
	v_rcp_f32_e32 v144, v144
	v_rcp_f32_e32 v145, v145
	v_rcp_f32_e32 v153, v153
	v_rcp_f32_e32 v255, v255
	v_mul_f32_e32 v76, v76, v222
	v_mul_f32_e32 v77, v77, v223
	v_mul_f32_e32 v78, v78, v224
	v_mul_f32_e32 v79, v79, v225
	v_mul_f32_e32 v68, v68, v144
	v_mul_f32_e32 v69, v69, v145
	v_mul_f32_e32 v70, v70, v153
	v_mul_f32_e32 v71, v71, v255
	v_mul_f32_e32 v76, v72, v76
	v_mul_f32_e32 v77, v73, v77
	v_mul_f32_e32 v78, v74, v78
	v_mul_f32_e32 v79, v75, v79
	v_mul_f32_e32 v68, v64, v68
	v_mul_f32_e32 v69, v65, v69
	v_mul_f32_e32 v70, v66, v70
	v_mul_f32_e32 v71, v67, v71
	v_cvt_pk_bf16_f32 v76, v76, v77
	v_cvt_pk_bf16_f32 v77, v78, v79
	v_cvt_pk_bf16_f32 v68, v68, v69
	v_cvt_pk_bf16_f32 v69, v70, v71
	global_store_dwordx2 v157, v[76:77], s[34:35]
	global_store_dwordx2 v157, v[68:69], s[34:35] offset:128
	v_mul_f32_e32 v60, v60, v210
	v_mul_f32_e32 v61, v61, v210
	v_mul_f32_e32 v62, v62, v210
	v_mul_f32_e32 v63, v63, v210
	v_mul_f32_e32 v52, v52, v210
	v_mul_f32_e32 v53, v53, v210
	v_mul_f32_e32 v54, v54, v210
	v_mul_f32_e32 v55, v55, v210
	v_mul_f32_e32 v56, v56, v210
	v_mul_f32_e32 v57, v57, v210
	v_mul_f32_e32 v58, v58, v210
	v_mul_f32_e32 v59, v59, v210
	v_mul_f32_e32 v48, v48, v210
	v_mul_f32_e32 v49, v49, v210
	v_mul_f32_e32 v50, v50, v210
	v_mul_f32_e32 v51, v51, v210
	v_mul_f32_e32 v222, 0xbfb8aa3b, v60
	v_mul_f32_e32 v223, 0xbfb8aa3b, v61
	v_mul_f32_e32 v224, 0xbfb8aa3b, v62
	v_mul_f32_e32 v225, 0xbfb8aa3b, v63
	v_mul_f32_e32 v144, 0xbfb8aa3b, v52
	v_mul_f32_e32 v145, 0xbfb8aa3b, v53
	v_mul_f32_e32 v153, 0xbfb8aa3b, v54
	v_mul_f32_e32 v255, 0xbfb8aa3b, v55
	v_exp_f32_e32 v222, v222
	v_exp_f32_e32 v223, v223
	v_exp_f32_e32 v224, v224
	v_exp_f32_e32 v225, v225
	v_exp_f32_e32 v144, v144
	v_exp_f32_e32 v145, v145
	v_exp_f32_e32 v153, v153
	v_exp_f32_e32 v255, v255
	v_add_f32_e32 v222, 1.0, v222
	v_add_f32_e32 v223, 1.0, v223
	v_add_f32_e32 v224, 1.0, v224
	v_add_f32_e32 v225, 1.0, v225
	v_add_f32_e32 v144, 1.0, v144
	v_add_f32_e32 v145, 1.0, v145
	v_add_f32_e32 v153, 1.0, v153
	v_add_f32_e32 v255, 1.0, v255
	v_rcp_f32_e32 v222, v222
	v_rcp_f32_e32 v223, v223
	v_rcp_f32_e32 v224, v224
	v_rcp_f32_e32 v225, v225
	v_rcp_f32_e32 v144, v144
	v_rcp_f32_e32 v145, v145
	v_rcp_f32_e32 v153, v153
	v_rcp_f32_e32 v255, v255
	v_mul_f32_e32 v60, v60, v222
	v_mul_f32_e32 v61, v61, v223
	v_mul_f32_e32 v62, v62, v224
	v_mul_f32_e32 v63, v63, v225
	v_mul_f32_e32 v52, v52, v144
	v_mul_f32_e32 v53, v53, v145
	v_mul_f32_e32 v54, v54, v153
	v_mul_f32_e32 v55, v55, v255
	v_mul_f32_e32 v60, v56, v60
	v_mul_f32_e32 v61, v57, v61
	v_mul_f32_e32 v62, v58, v62
	v_mul_f32_e32 v63, v59, v63
	v_mul_f32_e32 v52, v48, v52
	v_mul_f32_e32 v53, v49, v53
	v_mul_f32_e32 v54, v50, v54
	v_mul_f32_e32 v55, v51, v55
	v_cvt_pk_bf16_f32 v60, v60, v61
	v_cvt_pk_bf16_f32 v61, v62, v63
	v_cvt_pk_bf16_f32 v52, v52, v53
	v_cvt_pk_bf16_f32 v53, v54, v55
	global_store_dwordx2 v158, v[60:61], s[34:35]
	global_store_dwordx2 v158, v[52:53], s[34:35] offset:128
	v_mul_f32_e32 v44, v44, v211
	v_mul_f32_e32 v45, v45, v211
	v_mul_f32_e32 v46, v46, v211
	v_mul_f32_e32 v47, v47, v211
	v_mul_f32_e32 v36, v36, v211
	v_mul_f32_e32 v37, v37, v211
	v_mul_f32_e32 v38, v38, v211
	v_mul_f32_e32 v39, v39, v211
	v_mul_f32_e32 v40, v40, v211
	v_mul_f32_e32 v41, v41, v211
	v_mul_f32_e32 v42, v42, v211
	v_mul_f32_e32 v43, v43, v211
	v_mul_f32_e32 v32, v32, v211
	v_mul_f32_e32 v33, v33, v211
	v_mul_f32_e32 v34, v34, v211
	v_mul_f32_e32 v35, v35, v211
	v_mul_f32_e32 v222, 0xbfb8aa3b, v44
	v_mul_f32_e32 v223, 0xbfb8aa3b, v45
	v_mul_f32_e32 v224, 0xbfb8aa3b, v46
	v_mul_f32_e32 v225, 0xbfb8aa3b, v47
	v_mul_f32_e32 v144, 0xbfb8aa3b, v36
	v_mul_f32_e32 v145, 0xbfb8aa3b, v37
	v_mul_f32_e32 v153, 0xbfb8aa3b, v38
	v_mul_f32_e32 v255, 0xbfb8aa3b, v39
	v_exp_f32_e32 v222, v222
	v_exp_f32_e32 v223, v223
	v_exp_f32_e32 v224, v224
	v_exp_f32_e32 v225, v225
	v_exp_f32_e32 v144, v144
	v_exp_f32_e32 v145, v145
	v_exp_f32_e32 v153, v153
	v_exp_f32_e32 v255, v255
	v_add_f32_e32 v222, 1.0, v222
	v_add_f32_e32 v223, 1.0, v223
	v_add_f32_e32 v224, 1.0, v224
	v_add_f32_e32 v225, 1.0, v225
	v_add_f32_e32 v144, 1.0, v144
	v_add_f32_e32 v145, 1.0, v145
	v_add_f32_e32 v153, 1.0, v153
	v_add_f32_e32 v255, 1.0, v255
	v_rcp_f32_e32 v222, v222
	v_rcp_f32_e32 v223, v223
	v_rcp_f32_e32 v224, v224
	v_rcp_f32_e32 v225, v225
	v_rcp_f32_e32 v144, v144
	v_rcp_f32_e32 v145, v145
	v_rcp_f32_e32 v153, v153
	v_rcp_f32_e32 v255, v255
	v_mul_f32_e32 v44, v44, v222
	v_mul_f32_e32 v45, v45, v223
	v_mul_f32_e32 v46, v46, v224
	v_mul_f32_e32 v47, v47, v225
	v_mul_f32_e32 v36, v36, v144
	v_mul_f32_e32 v37, v37, v145
	v_mul_f32_e32 v38, v38, v153
	v_mul_f32_e32 v39, v39, v255
	v_mul_f32_e32 v44, v40, v44
	v_mul_f32_e32 v45, v41, v45
	v_mul_f32_e32 v46, v42, v46
	v_mul_f32_e32 v47, v43, v47
	v_mul_f32_e32 v36, v32, v36
	v_mul_f32_e32 v37, v33, v37
	v_mul_f32_e32 v38, v34, v38
	v_mul_f32_e32 v39, v35, v39
	v_cvt_pk_bf16_f32 v44, v44, v45
	v_cvt_pk_bf16_f32 v45, v46, v47
	v_cvt_pk_bf16_f32 v36, v36, v37
	v_cvt_pk_bf16_f32 v37, v38, v39
	global_store_dwordx2 v159, v[44:45], s[34:35]
	global_store_dwordx2 v159, v[36:37], s[34:35] offset:128
	v_mul_f32_e32 v28, v28, v212
	v_mul_f32_e32 v29, v29, v212
	v_mul_f32_e32 v30, v30, v212
	v_mul_f32_e32 v31, v31, v212
	v_mul_f32_e32 v20, v20, v212
	v_mul_f32_e32 v21, v21, v212
	v_mul_f32_e32 v22, v22, v212
	v_mul_f32_e32 v23, v23, v212
	v_mul_f32_e32 v24, v24, v212
	v_mul_f32_e32 v25, v25, v212
	v_mul_f32_e32 v26, v26, v212
	v_mul_f32_e32 v27, v27, v212
	v_mul_f32_e32 v16, v16, v212
	v_mul_f32_e32 v17, v17, v212
	v_mul_f32_e32 v18, v18, v212
	v_mul_f32_e32 v19, v19, v212
	v_mul_f32_e32 v222, 0xbfb8aa3b, v28
	v_mul_f32_e32 v223, 0xbfb8aa3b, v29
	v_mul_f32_e32 v224, 0xbfb8aa3b, v30
	v_mul_f32_e32 v225, 0xbfb8aa3b, v31
	v_mul_f32_e32 v144, 0xbfb8aa3b, v20
	v_mul_f32_e32 v145, 0xbfb8aa3b, v21
	v_mul_f32_e32 v153, 0xbfb8aa3b, v22
	v_mul_f32_e32 v255, 0xbfb8aa3b, v23
	v_exp_f32_e32 v222, v222
	v_exp_f32_e32 v223, v223
	v_exp_f32_e32 v224, v224
	v_exp_f32_e32 v225, v225
	v_exp_f32_e32 v144, v144
	v_exp_f32_e32 v145, v145
	v_exp_f32_e32 v153, v153
	v_exp_f32_e32 v255, v255
	v_add_f32_e32 v222, 1.0, v222
	v_add_f32_e32 v223, 1.0, v223
	v_add_f32_e32 v224, 1.0, v224
	v_add_f32_e32 v225, 1.0, v225
	v_add_f32_e32 v144, 1.0, v144
	v_add_f32_e32 v145, 1.0, v145
	v_add_f32_e32 v153, 1.0, v153
	v_add_f32_e32 v255, 1.0, v255
	v_rcp_f32_e32 v222, v222
	v_rcp_f32_e32 v223, v223
	v_rcp_f32_e32 v224, v224
	v_rcp_f32_e32 v225, v225
	v_rcp_f32_e32 v144, v144
	v_rcp_f32_e32 v145, v145
	v_rcp_f32_e32 v153, v153
	v_rcp_f32_e32 v255, v255
	v_mul_f32_e32 v28, v28, v222
	v_mul_f32_e32 v29, v29, v223
	v_mul_f32_e32 v30, v30, v224
	v_mul_f32_e32 v31, v31, v225
	v_mul_f32_e32 v20, v20, v144
	v_mul_f32_e32 v21, v21, v145
	v_mul_f32_e32 v22, v22, v153
	v_mul_f32_e32 v23, v23, v255
	v_mul_f32_e32 v28, v24, v28
	v_mul_f32_e32 v29, v25, v29
	v_mul_f32_e32 v30, v26, v30
	v_mul_f32_e32 v31, v27, v31
	v_mul_f32_e32 v20, v16, v20
	v_mul_f32_e32 v21, v17, v21
	v_mul_f32_e32 v22, v18, v22
	v_mul_f32_e32 v23, v19, v23
	v_cvt_pk_bf16_f32 v28, v28, v29
	v_cvt_pk_bf16_f32 v29, v30, v31
	v_cvt_pk_bf16_f32 v20, v20, v21
	v_cvt_pk_bf16_f32 v21, v22, v23
	global_store_dwordx2 v160, v[28:29], s[34:35]
	global_store_dwordx2 v160, v[20:21], s[34:35] offset:128
	v_mul_f32_e32 v12, v12, v213
	v_mul_f32_e32 v13, v13, v213
	v_mul_f32_e32 v14, v14, v213
	v_mul_f32_e32 v15, v15, v213
	v_mul_f32_e32 v4, v4, v213
	v_mul_f32_e32 v5, v5, v213
	v_mul_f32_e32 v6, v6, v213
	v_mul_f32_e32 v7, v7, v213
	v_mul_f32_e32 v8, v8, v213
	v_mul_f32_e32 v9, v9, v213
	v_mul_f32_e32 v10, v10, v213
	v_mul_f32_e32 v11, v11, v213
	v_mul_f32_e32 v0, v0, v213
	v_mul_f32_e32 v1, v1, v213
	v_mul_f32_e32 v2, v2, v213
	v_mul_f32_e32 v3, v3, v213
	v_mul_f32_e32 v222, 0xbfb8aa3b, v12
	v_mul_f32_e32 v223, 0xbfb8aa3b, v13
	v_mul_f32_e32 v224, 0xbfb8aa3b, v14
	v_mul_f32_e32 v225, 0xbfb8aa3b, v15
	v_mul_f32_e32 v144, 0xbfb8aa3b, v4
	v_mul_f32_e32 v145, 0xbfb8aa3b, v5
	v_mul_f32_e32 v153, 0xbfb8aa3b, v6
	v_mul_f32_e32 v255, 0xbfb8aa3b, v7
	v_exp_f32_e32 v222, v222
	v_exp_f32_e32 v223, v223
	v_exp_f32_e32 v224, v224
	v_exp_f32_e32 v225, v225
	v_exp_f32_e32 v144, v144
	v_exp_f32_e32 v145, v145
	v_exp_f32_e32 v153, v153
	v_exp_f32_e32 v255, v255
	v_add_f32_e32 v222, 1.0, v222
	v_add_f32_e32 v223, 1.0, v223
	v_add_f32_e32 v224, 1.0, v224
	v_add_f32_e32 v225, 1.0, v225
	v_add_f32_e32 v144, 1.0, v144
	v_add_f32_e32 v145, 1.0, v145
	v_add_f32_e32 v153, 1.0, v153
	v_add_f32_e32 v255, 1.0, v255
	v_rcp_f32_e32 v222, v222
	v_rcp_f32_e32 v223, v223
	v_rcp_f32_e32 v224, v224
	v_rcp_f32_e32 v225, v225
	v_rcp_f32_e32 v144, v144
	v_rcp_f32_e32 v145, v145
	v_rcp_f32_e32 v153, v153
	v_rcp_f32_e32 v255, v255
	v_mul_f32_e32 v12, v12, v222
	v_mul_f32_e32 v13, v13, v223
	v_mul_f32_e32 v14, v14, v224
	v_mul_f32_e32 v15, v15, v225
	v_mul_f32_e32 v4, v4, v144
	v_mul_f32_e32 v5, v5, v145
	v_mul_f32_e32 v6, v6, v153
	v_mul_f32_e32 v7, v7, v255
	v_mul_f32_e32 v12, v8, v12
	v_mul_f32_e32 v13, v9, v13
	v_mul_f32_e32 v14, v10, v14
	v_mul_f32_e32 v15, v11, v15
	v_mul_f32_e32 v4, v0, v4
	v_mul_f32_e32 v5, v1, v5
	v_mul_f32_e32 v6, v2, v6
	v_mul_f32_e32 v7, v3, v7
	v_cvt_pk_bf16_f32 v12, v12, v13
	v_cvt_pk_bf16_f32 v13, v14, v15
	v_cvt_pk_bf16_f32 v4, v4, v5
	v_cvt_pk_bf16_f32 v5, v6, v7
	global_store_dwordx2 v161, v[12:13], s[34:35]
	global_store_dwordx2 v161, v[4:5], s[34:35] offset:128
	s_andn2_b64 vcc, exec, s[6:7]
	s_mov_b64 s[6:7], -1
	s_cbranch_vccnz .LBB0_543
	s_andn2_b64 vcc, exec, s[14:15]
	s_cbranch_vccnz .LBB0_542
	s_barrier
	s_branch .LBB0_542
